# tile-queue item tops (proj, attention, wo, peer_q): the workgroup barrier in front of the ticket draw removed; the barrier after the ticket broadcast already orders the LDS ticket slot and the next ti
# baseline (speedup 1.0000x reference)
; #define tid_opaque() tid_from(WAVE_S)
; DI int next_item(unsigned* ctr, const int WAVE_S) {
;   __shared__ int s_item;
;   __syncthreads();
;   if (tid_opaque() == 0) s_item = (int)__hip_atomic_fetch_add(ctr, 1u, __ATOMIC_RELAXED, __HIP_MEMORY_SCOPE_AGENT);
;   __syncthreads();
;   return s_item;
; }
.LBB0_72:
	v_mbcnt_lo_u32_b32 v2, -1, 0
	v_mbcnt_hi_u32_b32 v2, -1, v2
	s_nop 0
	v_cmp_eq_u32_e32 vcc, s80, v2
	s_and_saveexec_b64 s[18:19], vcc
	s_cbranch_execz .LBB0_76
	s_mov_b64 s[46:47], exec
	v_mbcnt_lo_u32_b32 v2, s46, 0
	v_mbcnt_hi_u32_b32 v2, s47, v2
	v_cmp_eq_u32_e32 vcc, 0, v2
	s_and_saveexec_b64 s[34:35], vcc
	s_cbranch_execz .LBB0_75
	s_bcnt1_i32_b64 s46, s[46:47]
	v_mov_b32_e32 v3, s46
	global_atomic_add v3, v1, v3, s[40:41] sc0

; #define tid_opaque() tid_from(WAVE_S)
; DI int next_item(unsigned* ctr, const int WAVE_S) {
;   __shared__ int s_item;
;   __syncthreads();
;   if (tid_opaque() == 0) s_item = (int)__hip_atomic_fetch_add(ctr, 1u, __ATOMIC_RELAXED, __HIP_MEMORY_SCOPE_AGENT);
;   __syncthreads();
;   return s_item;
; }
.LBB0_172:
	v_mbcnt_lo_u32_b32 v0, -1, 0
	v_mbcnt_hi_u32_b32 v0, -1, v0
	s_nop 0
	v_cmp_eq_u32_e32 vcc, s80, v0
	s_and_saveexec_b64 s[18:19], vcc
	s_cbranch_execz .LBB0_176
	s_mov_b64 s[44:45], exec
	v_mbcnt_lo_u32_b32 v0, s44, 0
	v_mbcnt_hi_u32_b32 v0, s45, v0
	v_cmp_eq_u32_e32 vcc, 0, v0
	s_and_saveexec_b64 s[34:35], vcc
	s_cbranch_execz .LBB0_175
	s_bcnt1_i32_b64 s28, s[44:45]
	v_mov_b32_e32 v2, s28
	global_atomic_add v2, v1, v2, s[40:41] sc0

; #define tid_opaque() tid_from(WAVE_S)
; DI int next_item(unsigned* ctr, const int WAVE_S) {
;   __shared__ int s_item;
;   __syncthreads();
;   if (tid_opaque() == 0) s_item = (int)__hip_atomic_fetch_add(ctr, 1u, __ATOMIC_RELAXED, __HIP_MEMORY_SCOPE_AGENT);
;   __syncthreads();
;   return s_item;
; }
.LBB0_254:
	v_mbcnt_lo_u32_b32 v0, -1, 0
	v_mbcnt_hi_u32_b32 v0, -1, v0
	s_nop 0
	v_cmp_eq_u32_e32 vcc, s80, v0
	s_and_saveexec_b64 s[18:19], vcc
	s_cbranch_execz .LBB0_258
	s_mov_b64 s[44:45], exec
	v_mbcnt_lo_u32_b32 v0, s44, 0
	v_mbcnt_hi_u32_b32 v0, s45, v0
	v_cmp_eq_u32_e32 vcc, 0, v0
	s_and_saveexec_b64 s[40:41], vcc
	s_cbranch_execz .LBB0_257
	s_bcnt1_i32_b64 s28, s[44:45]
	v_mov_b32_e32 v2, s28
	global_atomic_add v2, v1, v2, s[34:35] sc0

; #define tid_opaque() tid_from(WAVE_S)
; DI int next_item(unsigned* ctr, const int WAVE_S) {
;   __shared__ int s_item;
;   __syncthreads();
;   if (tid_opaque() == 0) s_item = (int)__hip_atomic_fetch_add(ctr, 1u, __ATOMIC_RELAXED, __HIP_MEMORY_SCOPE_AGENT);
;   __syncthreads();
;   return s_item;
; }
.LBB0_382:
	s_waitcnt lgkmcnt(14)
	v_mbcnt_lo_u32_b32 v0, -1, 0
	v_mbcnt_hi_u32_b32 v0, -1, v0
	s_nop 0
	v_cmp_eq_u32_e32 vcc, s80, v0
	s_and_saveexec_b64 s[18:19], vcc
	s_cbranch_execz .LBB0_386
	s_mov_b64 s[44:45], exec
	v_mbcnt_lo_u32_b32 v0, s44, 0
	v_mbcnt_hi_u32_b32 v0, s45, v0
	v_cmp_eq_u32_e32 vcc, 0, v0
	s_and_saveexec_b64 s[40:41], vcc
	s_cbranch_execz .LBB0_385
	s_bcnt1_i32_b64 s28, s[44:45]
	v_mov_b32_e32 v2, s28
	global_atomic_add v2, v1, v2, s[36:37] sc0
